# combined: attention wait fix + lazy rescale + permlane row-max + L0 out-proj wait removal
# speedup vs baseline: 1.0015x; 1.0015x over previous
; DEV void attn_unit(const Params& P, int b, int qb, int h) {
;     ...
;       float mx = s0[0];
; #pragma unroll
;       for (int r = 1; r < 16; ++r) mx = fmaxf(mx, s0[r]);
; #pragma unroll
;       for (int r = 0; r < 16; ++r) mx = fmaxf(mx, s1[r]);
;       mx = fmaxf(mx, __shfl_xor(mx, 32));
;       const float mn = fmaxf(m, mx);
;       const float alpha = __builtin_amdgcn_exp2f(m - mn);
;       m = mn;
;       float ls = 0.f;
; #pragma unroll
;       for (int r = 0; r < 16; ++r) { s0[r] = __builtin_amdgcn_exp2f(s0[r] - mn); s1[r] = __builtin_amdgcn_exp2f(s1[r] - mn); ls += s0[r] + s1[r]; }
;       l = l * alpha + ls;
;       if (__any(alpha != 1.f)) {
; #pragma unroll
;         for (int r = 0; r < 16; ++r) { o[0][r] *= alpha; o[1][r] *= alpha; }
;       }
.LBB0_187:
	s_or_b64 exec, exec, s[26:27]
	s_nop 6
	v_max_f32_e32 v126, v49, v49
	v_max_f32_e32 v148, v48, v48
	v_max_f32_e32 v126, v148, v126
	v_max3_f32 v126, v126, v50, v51
	v_max3_f32 v126, v126, v52, v53
	v_max3_f32 v126, v126, v54, v55
	v_max3_f32 v126, v126, v56, v57
	v_max3_f32 v126, v126, v58, v59
	v_max3_f32 v126, v126, v60, v61
	v_max3_f32 v126, v126, v62, v63
	v_max3_f32 v126, v126, v32, v33
	v_max3_f32 v126, v126, v34, v35
	v_max3_f32 v126, v126, v36, v37
	v_max3_f32 v126, v126, v38, v39
	v_max3_f32 v126, v126, v40, v41
	v_max3_f32 v126, v126, v42, v43
	v_max3_f32 v126, v126, v44, v45
	v_max3_f32 v126, v126, v46, v47
	v_mov_b32_e32 v148, v126
	s_nop 1
	v_permlane32_swap_b32_e32 v148, v126
	v_max3_f32 v148, v125, v126, v148
	v_sub_f32_e32 v233, v125, v148
	v_cmp_gt_f32_e32 vcc, 0xc1000000, v233
	v_cndmask_b32_e32 v148, v125, v148, vcc
	v_sub_f32_e32 v125, v125, v148
	v_exp_f32_e32 v126, v125
	s_nop 0
	v_cmp_neq_f32_e32 vcc, 1.0, v126
	s_cbranch_vccz .LBB0_182
	v_pk_mul_f32 v[14:15], v[14:15], v[126:127] op_sel_hi:[1,0]
	v_pk_mul_f32 v[12:13], v[12:13], v[126:127] op_sel_hi:[1,0]
	v_pk_mul_f32 v[10:11], v[10:11], v[126:127] op_sel_hi:[1,0]
	v_pk_mul_f32 v[8:9], v[8:9], v[126:127] op_sel_hi:[1,0]
	v_pk_mul_f32 v[6:7], v[6:7], v[126:127] op_sel_hi:[1,0]
	v_pk_mul_f32 v[4:5], v[4:5], v[126:127] op_sel_hi:[1,0]
	v_pk_mul_f32 v[2:3], v[2:3], v[126:127] op_sel_hi:[1,0]
	v_pk_mul_f32 v[0:1], v[0:1], v[126:127] op_sel_hi:[1,0]
	v_pk_mul_f32 v[30:31], v[30:31], v[126:127] op_sel_hi:[1,0]
	v_pk_mul_f32 v[28:29], v[28:29], v[126:127] op_sel_hi:[1,0]
	v_pk_mul_f32 v[26:27], v[26:27], v[126:127] op_sel_hi:[1,0]
	v_pk_mul_f32 v[24:25], v[24:25], v[126:127] op_sel_hi:[1,0]
	v_pk_mul_f32 v[22:23], v[22:23], v[126:127] op_sel_hi:[1,0]
	v_pk_mul_f32 v[20:21], v[20:21], v[126:127] op_sel_hi:[1,0]
	v_pk_mul_f32 v[18:19], v[18:19], v[126:127] op_sel_hi:[1,0]
	v_pk_mul_f32 v[16:17], v[16:17], v[126:127] op_sel_hi:[1,0]
	s_branch .LBB0_182
